# FP: work queue - each workgroup's first unit of a mixer phase is its blockIdx (no atomic at phase start), later pops take counter+512
# speedup vs baseline: 1.0097x; 1.0088x over previous
.Lfbp_out:
.LBB0_635:
	s_or_b64 exec, exec, s[0:1]
	v_mov_b32_e32 v255, -1
	s_lshl_b64 s[0:1], s[86:87], 2
	s_add_u32 s44, s80, s0
	s_addc_u32 s45, s81, s1
	s_lshl_b64 s[0:1], s[2:3], 2
	s_add_u32 s48, s80, s0
	s_addc_u32 s49, s81, s1
	s_lshl_b32 s86, s2, 6
	s_lshl_b64 s[56:57], s[2:3], 20
	s_lshl_b32 s26, s2, 8
	s_lshl_b64 s[74:75], s[2:3], 15
	v_readlane_b32 s4, v232, 6
	s_add_u32 s4, s4, s0
	v_readlane_b32 s0, v232, 7
	s_addc_u32 s5, s0, s1
	v_writelane_b32 v232, s4, 39
	s_lshl_b64 s[0:1], s[86:87], 2
	s_waitcnt lgkmcnt(0)
	v_writelane_b32 v232, s5, 40
	v_readlane_b32 s4, v234, 20
	v_readlane_b32 s14, v234, 30
	v_readlane_b32 s15, v234, 31
	s_add_u32 s92, s14, s0
	s_barrier
	s_addc_u32 s93, s15, s1
	v_readlane_b32 s0, v232, 8
	v_readlane_b32 s19, v234, 35
	s_add_u32 s27, s0, s56
	v_readlane_b32 s0, v232, 9
	s_addc_u32 s50, s0, s57
	s_mov_b64 s[84:85], 0
	s_movk_i32 s19, 0x70
	v_readlane_b32 s5, v234, 21
	v_readlane_b32 s6, v234, 22
	v_readlane_b32 s7, v234, 23
	v_readlane_b32 s8, v234, 24
	v_readlane_b32 s9, v234, 25
	v_readlane_b32 s10, v234, 26
	v_readlane_b32 s11, v234, 27
	v_readlane_b32 s12, v234, 28
	v_readlane_b32 s13, v234, 29
	v_readlane_b32 s16, v234, 32
	v_readlane_b32 s17, v234, 33
	v_readlane_b32 s18, v234, 34
	s_branch .LBB0_640

.LBB0_640:
	v_mov_b32_e32 v0, v156
	s_barrier
	s_nop 0
	v_cmp_eq_u32_e32 vcc, 0, v0
	s_and_saveexec_b64 s[0:1], vcc
	s_cbranch_execz .LBB0_644
	v_cmp_ne_u32_e32 vcc, -1, v255
	s_cbranch_vccnz .Lfp_atomic
	v_readlane_b32 s4, v232, 14
	v_mov_b32_e32 v255, 0
	s_lshr_b32 s4, s4, 2
	v_mov_b32_e32 v0, s4
	s_branch .Lfp_have
.Lfp_atomic:
	global_atomic_add v0, v1, v160, s[44:45] sc0
	s_waitcnt vmcnt(0)
	v_add_u32_e32 v0, 0x200, v0
.Lfp_have:
	ds_write_b32 v161, v0
